# mixer A dilated sites: QK^T MFMAs wait only for the K half of the LDS re-shape (V^T half stays queued until the row-max exchange waits in front of P*V); plus B window loop back-edge rotation
# speedup vs baseline: 1.0070x; 1.0014x over previous
.LBB0_619:
	v_lshl_add_u64 v[48:49], v[104:105], 0, v[208:209]
	v_add_co_u32_e32 v28, vcc, 0xc460000, v48
	v_lshl_add_u64 v[80:81], v[106:107], 0, v[208:209]
	s_nop 0
	v_addc_co_u32_e32 v29, vcc, 0, v49, vcc
	v_add_co_u32_e32 v36, vcc, 0xc440000, v48
	v_lshl_add_u64 v[236:237], v[28:29], 0, v[214:215]
	global_load_dwordx4 v[24:27], v[236:237], off offset:128
	s_nop 0
	global_load_dwordx4 v[28:31], v[28:29], off offset:128
	v_addc_co_u32_e32 v37, vcc, 0, v49, vcc
	v_add_co_u32_e32 v44, vcc, 0xc420000, v48
	v_lshl_add_u64 v[236:237], v[36:37], 0, v[214:215]
	global_load_dwordx4 v[32:35], v[236:237], off offset:128
	s_nop 0
	global_load_dwordx4 v[36:39], v[36:37], off offset:128
	v_addc_co_u32_e32 v45, vcc, 0, v49, vcc
	v_add_co_u32_e32 v52, vcc, 0xc400000, v48
	v_lshl_add_u64 v[236:237], v[44:45], 0, v[214:215]
	global_load_dwordx4 v[40:43], v[236:237], off offset:128
	s_nop 0
	global_load_dwordx4 v[44:47], v[44:45], off offset:128
	v_addc_co_u32_e32 v53, vcc, 0, v49, vcc
	v_add_co_u32_e32 v60, vcc, 0xa00e000, v80
	v_lshl_add_u64 v[236:237], v[52:53], 0, v[214:215]
	global_load_dwordx4 v[48:51], v[236:237], off offset:128
	s_nop 0
	global_load_dwordx4 v[52:55], v[52:53], off offset:128
	v_addc_co_u32_e32 v61, vcc, 0, v81, vcc
	v_add_co_u32_e32 v64, vcc, 0xa00c000, v80
	v_lshl_add_u64 v[236:237], v[60:61], 0, v[232:233]
	global_load_dwordx4 v[56:59], v[236:237], off
	global_load_dwordx4 v[68:71], v[60:61], off
	v_addc_co_u32_e32 v65, vcc, 0, v81, vcc
	v_add_co_u32_e32 v76, vcc, 0xa00a000, v80
	v_lshl_add_u64 v[236:237], v[64:65], 0, v[232:233]
	global_load_dwordx4 v[60:63], v[236:237], off
	global_load_dwordx4 v[72:75], v[64:65], off
	v_addc_co_u32_e32 v77, vcc, 0, v81, vcc
	v_add_co_u32_e32 v84, vcc, 0xa008000, v80
	v_lshl_add_u64 v[236:237], v[76:77], 0, v[232:233]
	global_load_dwordx4 v[64:67], v[236:237], off
	s_nop 0
	global_load_dwordx4 v[76:79], v[76:77], off
	v_addc_co_u32_e32 v85, vcc, 0, v81, vcc
	v_lshl_add_u64 v[236:237], v[84:85], 0, v[232:233]
	global_load_dwordx4 v[80:83], v[236:237], off
	s_nop 0
	global_load_dwordx4 v[84:87], v[84:85], off
	v_add_u32_e32 v95, 35, v116
	v_cmp_gt_u32_e64 s[22:23], s47, v95
	v_add_u32_e32 v95, 64, v97
	v_add_u32_e32 v122, 0xffffff90, v116
	v_add_u32_e32 v123, 0xffffff8f, v116
	v_cmp_gt_u32_e64 s[20:21], s88, v95
	v_add_u32_e32 v118, 0xffffffa0, v116
	v_add_u32_e32 v119, 0xffffff9f, v116
	v_cmp_gt_u32_e64 s[8:9], s88, v122
	v_cmp_gt_u32_e32 vcc, s88, v123
	v_cndmask_b32_e64 v95, 2, 0, s[20:21]
	v_cmp_gt_u32_e64 s[16:17], s88, v118
	v_cmp_gt_u32_e64 s[18:19], s88, v119
	v_cndmask_b32_e64 v122, 64, 0, s[8:9]
	v_cndmask_b32_e64 v123, v244, 0, vcc
	v_cndmask_b32_e64 v118, 4, 0, s[16:17]
	v_cndmask_b32_e64 v119, 8, 0, s[18:19]
	v_add_u32_e32 v120, 0xffffff92, v116
	v_add_u32_e32 v121, 0xffffff91, v116
	v_or3_b32 v95, v122, v123, v95
	v_cmp_gt_u32_e64 s[6:7], s88, v120
	v_cmp_gt_u32_e64 s[10:11], s88, v121
	v_or3_b32 v95, v118, v119, v95
	v_add_u32_e32 v118, 3, v116
	v_add_u32_e32 v119, 2, v116
	v_cndmask_b32_e64 v120, 16, 0, s[6:7]
	v_cndmask_b32_e64 v121, 32, 0, s[10:11]
	v_cmp_gt_u32_e64 s[14:15], s47, v118
	v_cmp_gt_u32_e64 s[12:13], s47, v119
	v_or3_b32 v95, v120, v121, v95
	v_cndmask_b32_e64 v118, 0, v245, s[14:15]
	v_cndmask_b32_e64 v119, 0, v240, s[12:13]
	v_or3_b32 v95, v118, v95, v119
	v_add_u32_e32 v118, 1, v116
	v_cmp_gt_u32_e64 s[24:25], s47, v118
	v_add_u32_e32 v120, -13, v116
	v_add_u32_e32 v121, -14, v116
	v_cndmask_b32_e64 v118, 0, v246, s[24:25]
	v_cmp_gt_u32_e64 s[24:25], s47, v116
	v_add_u32_e32 v122, -15, v116
	v_add_u32_e32 v123, -16, v116
	v_cndmask_b32_e64 v119, 0, v247, s[24:25]
	v_cmp_gt_u32_e64 s[24:25], s47, v120
	v_or_b32_e32 v118, v118, v119
	v_or_b32_e32 v119, v118, v95
	v_cndmask_b32_e64 v120, 0, v248, s[24:25]
	v_cmp_gt_u32_e64 s[24:25], s47, v121
	s_add_i32 s58, s58, 2
	s_min_i32 s92, s58, s57
	s_waitcnt vmcnt(0) lgkmcnt(0)
	ds_write_b128 v234, v[68:71]
	ds_write_b128 v234, v[56:59] offset:1280
	ds_write_b128 v234, v[72:75] offset:2560
	ds_write_b128 v234, v[60:63] offset:3840
	ds_write_b128 v234, v[76:79] offset:5120
	ds_write_b128 v234, v[64:67] offset:6400
	ds_write_b128 v234, v[84:87] offset:7680
	ds_write_b128 v234, v[80:83] offset:8960
	ds_read_b128 v[68:71], v235
	ds_read_b128 v[56:59], v235 offset:64
	ds_read_b128 v[72:75], v235 offset:2560
	ds_read_b128 v[60:63], v235 offset:2624
	ds_read_b128 v[76:79], v235 offset:5120
	ds_read_b128 v[64:67], v235 offset:5184
	ds_read_b128 v[84:87], v235 offset:7680
	ds_read_b128 v[80:83], v235 offset:7744
	ds_write_b128 v234, v[28:31]
	ds_write_b128 v234, v[24:27] offset:1280
	ds_write_b128 v234, v[36:39] offset:2560
	ds_write_b128 v234, v[32:35] offset:3840
	ds_write_b128 v234, v[44:47] offset:5120
	ds_write_b128 v234, v[40:43] offset:6400
	ds_write_b128 v234, v[52:55] offset:7680
	ds_write_b128 v234, v[48:51] offset:8960
	ds_read_b128 v[28:31], v235
	ds_read_b128 v[24:27], v235 offset:64
	ds_read_b128 v[36:39], v235 offset:2560
	ds_read_b128 v[32:35], v235 offset:2624
	ds_read_b128 v[44:47], v235 offset:5120
	ds_read_b128 v[40:43], v235 offset:5184
	ds_read_b128 v[52:55], v235 offset:7680
	ds_read_b128 v[48:51], v235 offset:7744
	s_waitcnt lgkmcnt(15)
	v_mfma_f32_16x16x32_bf16 v[68:71], v[68:71], v[16:19], 0
	v_cndmask_b32_e64 v121, 0, v249, s[24:25]
	v_cmp_gt_u32_e64 s[24:25], s47, v122
	v_or_b32_e32 v120, v120, v121
	v_mfma_f32_16x16x32_bf16 v[84:87], v[84:87], v[16:19], 0
	v_cndmask_b32_e64 v122, 0, v250, s[24:25]
	v_cmp_gt_u32_e64 s[24:25], s47, v123
	v_or_b32_e32 v121, v120, v119
	v_mfma_f32_16x16x32_bf16 v[76:79], v[76:79], v[16:19], 0
	v_cndmask_b32_e64 v123, 0, v251, s[24:25]
	v_or_b32_e32 v122, v122, v123
	s_lshl_b32 s54, s92, 6
	v_mfma_f32_16x16x32_bf16 v[72:75], v[72:75], v[16:19], 0
	s_cmp_gt_i32 s58, s57
	v_add_u32_e32 v97, 0x80, v97
	v_add_u32_e32 v116, 0xffffff80, v116
	v_mfma_f32_16x16x32_bf16 v[80:83], v[80:83], v[20:23], v[84:87]
	v_mfma_f32_16x16x32_bf16 v[64:67], v[64:67], v[20:23], v[76:79]
	v_mfma_f32_16x16x32_bf16 v[60:63], v[60:63], v[20:23], v[72:75]
	v_mfma_f32_16x16x32_bf16 v[56:59], v[56:59], v[20:23], v[68:71]
	s_nop 4
	v_mul_f32_e32 v72, 0x3e38aa3b, v83
	v_bitop3_b32 v73, v118, s95, v95 bitop3:0xc8
	v_cndmask_b32_e64 v72, v72, v241, s[18:19]
	v_mul_f32_e32 v68, 0x3e38aa3b, v80
	v_mul_f32_e32 v69, 0x3e38aa3b, v81
	v_cndmask_b32_e64 v68, v241, v68, s[22:23]
	v_cndmask_b32_e64 v69, v69, v241, s[20:21]
	v_mul_f32_e32 v71, 0x3e38aa3b, v82
	v_max3_f32 v70, v68, s71, v69
	v_cndmask_b32_e64 v71, v71, v241, s[16:17]
	v_mul_f32_e32 v64, 0x3e38aa3b, v64
	v_mul_f32_e32 v65, 0x3e38aa3b, v65
	v_cmp_eq_u32_e64 s[36:37], 0, v73
	v_bitop3_b32 v73, v118, s48, v95 bitop3:0xc8
	v_max3_f32 v70, v70, v71, v72
	v_cndmask_b32_e64 v64, v64, v241, s[6:7]
	v_cndmask_b32_e64 v65, v65, v241, s[10:11]
	v_mul_f32_e32 v66, 0x3e38aa3b, v66
	v_mul_f32_e32 v67, 0x3e38aa3b, v67
	v_cmp_eq_u32_e64 s[26:27], 0, v73
	v_bitop3_b32 v73, v120, s90, v119 bitop3:0xc8
	v_max3_f32 v70, v70, v64, v65
	v_cndmask_b32_e64 v66, v66, v241, s[8:9]
	v_cndmask_b32_e32 v67, v67, v241, vcc
	v_mul_f32_e32 v60, 0x3e38aa3b, v60
	v_mul_f32_e32 v61, 0x3e38aa3b, v61
	v_cmp_eq_u32_e64 s[34:35], 0, v73
	v_bitop3_b32 v73, v120, s83, v119 bitop3:0xc8
	v_max3_f32 v70, v70, v66, v67
	v_cndmask_b32_e64 v60, v241, v60, s[14:15]
	v_cndmask_b32_e64 v61, v241, v61, s[12:13]
	v_mul_f32_e32 v62, 0x3e38aa3b, v62
	v_mul_f32_e32 v63, 0x3e38aa3b, v63
	v_cmp_eq_u32_e64 s[30:31], 0, v73
	v_bitop3_b32 v73, v122, s50, v121 bitop3:0xc8
	v_max3_f32 v70, v70, v60, v61
	v_cndmask_b32_e64 v62, v62, v241, s[36:37]
	v_cndmask_b32_e64 v63, v63, v241, s[26:27]
	v_mul_f32_e32 v56, 0x3e38aa3b, v56
	v_mul_f32_e32 v57, 0x3e38aa3b, v57
	v_cmp_eq_u32_e64 s[28:29], 0, v73
	v_bitop3_b32 v73, v122, s82, v121 bitop3:0xc8
	v_max3_f32 v70, v70, v62, v63
	v_cndmask_b32_e64 v56, v56, v241, s[34:35]
	v_cndmask_b32_e64 v57, v57, v241, s[30:31]
	v_mul_f32_e32 v58, 0x3e38aa3b, v58
	v_cmp_eq_u32_e64 s[24:25], 0, v73
	v_mul_f32_e32 v59, 0x3e38aa3b, v59
	v_max3_f32 v70, v70, v56, v57
	v_cndmask_b32_e64 v58, v58, v241, s[28:29]
	v_cndmask_b32_e64 v59, v59, v241, s[24:25]
	v_max3_f32 v70, v70, v58, v59
	ds_bpermute_b32 v73, v109, v70
	s_waitcnt lgkmcnt(0)
	v_max_f32_e32 v73, v73, v73
	v_max_f32_e32 v70, v70, v73
	ds_bpermute_b32 v73, v108, v70
	s_waitcnt lgkmcnt(0)
	v_max3_f32 v118, v117, v70, v73
	v_sub_f32_e32 v68, v68, v118
	v_exp_f32_e32 v68, v68
	v_sub_f32_e32 v69, v69, v118
	v_exp_f32_e32 v69, v69
	v_sub_f32_e32 v71, v71, v118
	v_exp_f32_e32 v71, v71
	v_sub_f32_e32 v72, v72, v118
	v_exp_f32_e32 v72, v72
	v_sub_f32_e32 v64, v64, v118
	v_cndmask_b32_e64 v68, 0, v68, s[22:23]
	v_exp_f32_e32 v64, v64
	v_sub_f32_e32 v65, v65, v118
	v_add_f32_e32 v73, 0, v68
	v_cndmask_b32_e64 v69, v69, 0, s[20:21]
	v_exp_f32_e32 v65, v65
	v_sub_f32_e32 v66, v66, v118
	v_sub_f32_e32 v57, v57, v118
	v_add_f32_e32 v73, v69, v73
	v_cndmask_b32_e64 v71, v71, 0, s[16:17]
	v_exp_f32_e32 v66, v66
	v_sub_f32_e32 v67, v67, v118
	v_exp_f32_e32 v57, v57
	v_add_f32_e32 v73, v71, v73
	v_cndmask_b32_e64 v72, v72, 0, s[18:19]
	v_exp_f32_e32 v67, v67
	v_sub_f32_e32 v60, v60, v118
	v_add_f32_e32 v73, v72, v73
	v_cndmask_b32_e64 v74, v64, 0, s[6:7]
	v_exp_f32_e32 v60, v60
	v_sub_f32_e32 v61, v61, v118
	v_add_f32_e32 v64, v74, v73
	v_cndmask_b32_e64 v65, v65, 0, s[10:11]
	v_exp_f32_e32 v61, v61
	v_sub_f32_e32 v62, v62, v118
	v_add_f32_e32 v64, v65, v64
	v_cndmask_b32_e64 v66, v66, 0, s[8:9]
	v_exp_f32_e32 v62, v62
	v_sub_f32_e32 v63, v63, v118
	v_cndmask_b32_e64 v75, v57, 0, s[30:31]
	v_sub_f32_e32 v57, v58, v118
	v_add_f32_e32 v64, v66, v64
	v_cndmask_b32_e64 v67, v67, 0, vcc
	v_exp_f32_e32 v63, v63
	v_sub_f32_e32 v56, v56, v118
	v_exp_f32_e32 v57, v57
	v_add_f32_e32 v64, v67, v64
	v_cndmask_b32_e64 v60, 0, v60, s[14:15]
	v_exp_f32_e32 v56, v56
	v_add_f32_e32 v64, v60, v64
	v_cndmask_b32_e64 v61, 0, v61, s[12:13]
	v_add_f32_e32 v64, v61, v64
	v_cndmask_b32_e64 v62, v62, 0, s[36:37]
	v_add_f32_e32 v64, v62, v64
	v_cndmask_b32_e64 v63, v63, 0, s[26:27]
	v_cndmask_b32_e64 v76, v57, 0, s[28:29]
	v_sub_f32_e32 v57, v59, v118
	v_sub_f32_e32 v70, v117, v118
	v_add_f32_e32 v64, v63, v64
	v_cndmask_b32_e64 v73, v56, 0, s[34:35]
	v_exp_f32_e32 v57, v57
	v_add_f32_e32 v56, v73, v64
	v_exp_f32_e32 v64, v70
	v_add_f32_e32 v56, v75, v56
	v_add_f32_e32 v56, v76, v56
	v_cndmask_b32_e64 v77, v57, 0, s[24:25]
	v_add_f32_e32 v119, v77, v56
	v_cvt_pk_bf16_f32 v56, v68, v69
	v_cvt_pk_bf16_f32 v57, v71, v72
	v_cvt_pk_bf16_f32 v58, v74, v65
	v_cvt_pk_bf16_f32 v59, v66, v67
	v_pk_mul_f32 v[10:11], v[10:11], v[64:65] op_sel_hi:[1,0]
	v_pk_mul_f32 v[8:9], v[8:9], v[64:65] op_sel_hi:[1,0]
	v_pk_mul_f32 v[14:15], v[14:15], v[64:65] op_sel_hi:[1,0]
	v_pk_mul_f32 v[12:13], v[12:13], v[64:65] op_sel_hi:[1,0]
	v_pk_mul_f32 v[6:7], v[6:7], v[64:65] op_sel_hi:[1,0]
	v_pk_mul_f32 v[4:5], v[4:5], v[64:65] op_sel_hi:[1,0]
	v_pk_mul_f32 v[2:3], v[2:3], v[64:65] op_sel_hi:[1,0]
	v_pk_mul_f32 v[0:1], v[0:1], v[64:65] op_sel_hi:[1,0]
	v_mfma_f32_16x16x32_bf16 v[8:11], v[52:55], v[56:59], v[8:11]
	v_cvt_pk_bf16_f32 v60, v60, v61
	v_cvt_pk_bf16_f32 v61, v62, v63
	v_cvt_pk_bf16_f32 v62, v73, v75
	v_mfma_f32_16x16x32_bf16 v[12:15], v[44:47], v[56:59], v[12:15]
	v_cvt_pk_bf16_f32 v63, v76, v77
	s_mov_b64 s[6:7], 0x100
	v_fmac_f32_e32 v119, v114, v64
	v_mfma_f32_16x16x32_bf16 v[4:7], v[36:39], v[56:59], v[4:7]
	v_lshl_add_u64 v[104:105], v[104:105], 0, s[6:7]
	s_mov_b64 s[6:7], 0x10000
	v_lshl_add_u64 v[106:107], v[106:107], 0, s[6:7]
	v_mfma_f32_16x16x32_bf16 v[0:3], v[28:31], v[56:59], v[0:3]
	s_cselect_b64 s[6:7], -1, 0
	v_mov_b32_e32 v117, v118
	v_mov_b32_e32 v114, v119
	v_mfma_f32_16x16x32_bf16 v[8:11], v[48:51], v[60:63], v[8:11]
	v_mfma_f32_16x16x32_bf16 v[12:15], v[40:43], v[60:63], v[12:15]
	v_mfma_f32_16x16x32_bf16 v[4:7], v[32:35], v[60:63], v[4:7]
	v_mfma_f32_16x16x32_bf16 v[0:3], v[24:27], v[60:63], v[0:3]
	s_andn2_b64 vcc, exec, s[6:7]
	s_cbranch_vccz .LBB0_623
.LBB0_620:
	s_lshl_b64 s[6:7], s[92:93], 15
	v_lshl_add_u64 v[24:25], v[100:101], 0, s[6:7]
	v_lshl_add_u64 v[24:25], v[212:213], 1, v[24:25]
	v_add_co_u32_e32 v26, vcc, s50, v24
	s_movk_i32 s6, 0x6000
	s_nop 0
	v_addc_co_u32_e32 v27, vcc, 0, v25, vcc
	v_lshl_add_u64 v[236:237], v[26:27], 0, v[232:233]
	global_load_dwordx4 v[56:59], v[236:237], off
	global_load_dwordx4 v[72:75], v[26:27], off
	v_add_co_u32_e32 v26, vcc, s83, v24
	s_mov_b32 s55, s93
	s_nop 0
	v_addc_co_u32_e32 v27, vcc, 0, v25, vcc
	v_lshl_add_u64 v[236:237], v[26:27], 0, v[232:233]
	global_load_dwordx4 v[60:63], v[236:237], off
	global_load_dwordx4 v[76:79], v[26:27], off
	v_lshl_add_u64 v[236:237], v[24:25], 0, v[232:233]
	global_load_dwordx4 v[64:67], v[236:237], off
	global_load_dwordx4 v[80:83], v[24:25], off
	v_add_co_u32_e32 v24, vcc, s6, v24
	s_mov_b32 s6, 0x40000
	s_nop 0
	v_addc_co_u32_e32 v25, vcc, 0, v25, vcc
	global_load_dwordx4 v[120:123], v[24:25], off
	v_lshl_add_u64 v[236:237], v[24:25], 0, v[232:233]
	global_load_dwordx4 v[68:71], v[236:237], off
	v_lshl_add_u64 v[24:25], s[54:55], 1, v[102:103]
	v_add_co_u32_e32 v26, vcc, s0, v24
	global_load_dwordx4 v[52:55], v[24:25], off
	v_lshl_add_u64 v[236:237], v[24:25], 0, v[214:215]
	global_load_dwordx4 v[48:51], v[236:237], off
	v_addc_co_u32_e32 v27, vcc, 0, v25, vcc
	global_load_dwordx4 v[44:47], v[26:27], off
	v_lshl_add_u64 v[236:237], v[26:27], 0, v[214:215]
	global_load_dwordx4 v[40:43], v[236:237], off
	v_add_co_u32_e32 v26, vcc, s6, v24
	v_add_u32_e32 v95, 0x63, v116
	s_nop 0
	v_addc_co_u32_e32 v27, vcc, 0, v25, vcc
	v_add_co_u32_e32 v28, vcc, s76, v24
	global_load_dwordx4 v[36:39], v[26:27], off
	v_lshl_add_u64 v[236:237], v[26:27], 0, v[214:215]
	global_load_dwordx4 v[32:35], v[236:237], off
	v_addc_co_u32_e32 v29, vcc, 0, v25, vcc
	global_load_dwordx4 v[24:27], v[28:29], off
	s_nop 0
	v_lshl_add_u64 v[236:237], v[28:29], 0, v[214:215]
	global_load_dwordx4 v[28:31], v[236:237], off
	v_cmp_gt_u32_e64 s[20:21], s88, v97
	v_add_u32_e32 v114, 0x61, v116
	v_add_u32_e32 v117, 0x60, v116
	v_cmp_gt_u32_e64 s[22:23], s47, v95
	v_cndmask_b32_e64 v95, 2, 0, s[20:21]
	v_cmp_lt_u32_e64 s[12:13], s49, v114
	v_cmp_lt_u32_e64 s[18:19], s49, v117
	s_cmp_ge_i32 s58, s57
	v_cndmask_b32_e64 v114, 4, 0, s[12:13]
	v_cndmask_b32_e64 v117, 8, 0, s[18:19]
	s_waitcnt vmcnt(0) lgkmcnt(0)
	ds_write_b128 v234, v[72:75]
	ds_write_b128 v234, v[56:59] offset:1280
	ds_write_b128 v234, v[76:79] offset:2560
	ds_write_b128 v234, v[60:63] offset:3840
	ds_write_b128 v234, v[80:83] offset:5120
	ds_write_b128 v234, v[64:67] offset:6400
	ds_write_b128 v234, v[120:123] offset:7680
	ds_write_b128 v234, v[68:71] offset:8960
	ds_read_b128 v[72:75], v235
	ds_read_b128 v[56:59], v235 offset:64
	ds_read_b128 v[76:79], v235 offset:2560
	ds_read_b128 v[60:63], v235 offset:2624
	ds_read_b128 v[80:83], v235 offset:5120
	ds_read_b128 v[64:67], v235 offset:5184
	ds_read_b128 v[120:123], v235 offset:7680
	ds_read_b128 v[68:71], v235 offset:7744
	ds_write_b128 v234, v[52:55]
	ds_write_b128 v234, v[48:51] offset:1280
	ds_write_b128 v234, v[44:47] offset:2560
	ds_write_b128 v234, v[40:43] offset:3840
	ds_write_b128 v234, v[36:39] offset:5120
	ds_write_b128 v234, v[32:35] offset:6400
	ds_write_b128 v234, v[24:27] offset:7680
	ds_write_b128 v234, v[28:31] offset:8960
	ds_read_b128 v[52:55], v235
	ds_read_b128 v[48:51], v235 offset:64
	ds_read_b128 v[44:47], v235 offset:2560
	ds_read_b128 v[40:43], v235 offset:2624
	ds_read_b128 v[36:39], v235 offset:5120
	ds_read_b128 v[32:35], v235 offset:5184
	ds_read_b128 v[24:27], v235 offset:7680
	ds_read_b128 v[28:31], v235 offset:7744
	s_waitcnt lgkmcnt(15)
	v_mfma_f32_16x16x32_bf16 v[84:87], v[80:83], v[16:19], 0
	v_mfma_f32_16x16x32_bf16 v[80:83], v[76:79], v[16:19], 0
	v_mfma_f32_16x16x32_bf16 v[76:79], v[72:75], v[16:19], 0
	v_mfma_f32_16x16x32_bf16 v[72:75], v[120:123], v[16:19], 0
	v_add_u32_e32 v122, 0x51, v116
	v_add_u32_e32 v123, 0x50, v116
	v_cmp_lt_u32_e64 s[8:9], s49, v122
	v_cmp_lt_u32_e32 vcc, s49, v123
	v_add_u32_e32 v120, 0x53, v116
	v_cndmask_b32_e64 v122, 64, 0, s[8:9]
	v_cndmask_b32_e64 v123, v244, 0, vcc
	v_add_u32_e32 v121, 0x52, v116
	v_or3_b32 v95, v95, v122, v123
	v_cmp_lt_u32_e64 s[6:7], s49, v120
	v_cmp_lt_u32_e64 s[10:11], s49, v121
	v_or3_b32 v95, v114, v117, v95
	v_add_u32_e32 v114, 0x43, v116
	v_add_u32_e32 v117, 0x42, v116
	v_cndmask_b32_e64 v120, 16, 0, s[6:7]
	v_cndmask_b32_e64 v121, 32, 0, s[10:11]
	v_cmp_gt_u32_e64 s[16:17], s47, v114
	v_cmp_gt_u32_e64 s[14:15], s47, v117
	v_or3_b32 v95, v120, v121, v95
	v_cndmask_b32_e64 v114, 0, v245, s[16:17]
	v_cndmask_b32_e64 v117, 0, v240, s[14:15]
	v_or3_b32 v95, v114, v95, v117
	v_add_u32_e32 v114, 0x41, v116
	v_mfma_f32_16x16x32_bf16 v[64:67], v[64:67], v[20:23], v[84:87]
	v_cmp_gt_u32_e64 s[24:25], s47, v114
	v_add_u32_e32 v117, 64, v116
	v_add_u32_e32 v120, 51, v116
	v_cndmask_b32_e64 v114, 0, v246, s[24:25]
	v_cmp_gt_u32_e64 s[24:25], s47, v117
	v_mfma_f32_16x16x32_bf16 v[60:63], v[60:63], v[20:23], v[80:83]
	v_add_u32_e32 v121, 50, v116
	v_cndmask_b32_e64 v117, 0, v247, s[24:25]
	v_cmp_gt_u32_e64 s[24:25], s47, v120
	v_or_b32_e32 v114, v114, v117
	v_add_u32_e32 v122, 49, v116
	v_cndmask_b32_e64 v120, 0, v248, s[24:25]
	v_cmp_gt_u32_e64 s[24:25], s47, v121
	v_mfma_f32_16x16x32_bf16 v[56:59], v[56:59], v[20:23], v[76:79]
	v_mul_f32_e32 v64, 0x3e38aa3b, v64
	v_mul_f32_e32 v65, 0x3e38aa3b, v65
	v_cndmask_b32_e64 v121, 0, v249, s[24:25]
	v_cmp_gt_u32_e64 s[24:25], s47, v122
	v_add_u32_e32 v123, 48, v116
	v_mfma_f32_16x16x32_bf16 v[68:71], v[68:71], v[20:23], v[72:75]
	v_cndmask_b32_e64 v64, v241, v64, s[22:23]
	v_cndmask_b32_e64 v65, v65, v241, s[20:21]
	v_mul_f32_e32 v66, 0x3e38aa3b, v66
	v_mul_f32_e32 v67, 0x3e38aa3b, v67
	v_bitop3_b32 v73, v114, s95, v95 bitop3:0xc8
	v_or_b32_e32 v117, v114, v95
	v_or_b32_e32 v120, v120, v121
	v_cndmask_b32_e64 v122, 0, v250, s[24:25]
	v_cmp_gt_u32_e64 s[24:25], s47, v123
	v_max3_f32 v72, v64, s71, v65
	v_cndmask_b32_e64 v66, v66, v241, s[12:13]
	v_cndmask_b32_e64 v67, v67, v241, s[18:19]
	v_mul_f32_e32 v60, 0x3e38aa3b, v60
	v_mul_f32_e32 v61, 0x3e38aa3b, v61
	v_cmp_eq_u32_e64 s[36:37], 0, v73
	v_bitop3_b32 v73, v114, s48, v95 bitop3:0xc8
	v_cndmask_b32_e64 v123, 0, v251, s[24:25]
	v_max3_f32 v72, v72, v66, v67
	v_cndmask_b32_e64 v60, v60, v241, s[6:7]
	v_cndmask_b32_e64 v61, v61, v241, s[10:11]
	v_mul_f32_e32 v62, 0x3e38aa3b, v62
	v_mul_f32_e32 v63, 0x3e38aa3b, v63
	v_cmp_eq_u32_e64 s[26:27], 0, v73
	v_bitop3_b32 v73, v120, s90, v117 bitop3:0xc8
	v_or_b32_e32 v121, v120, v117
	v_or_b32_e32 v122, v122, v123
	v_max3_f32 v72, v72, v60, v61
	v_cndmask_b32_e64 v62, v62, v241, s[8:9]
	v_cndmask_b32_e32 v63, v63, v241, vcc
	v_mul_f32_e32 v56, 0x3e38aa3b, v56
	v_mul_f32_e32 v57, 0x3e38aa3b, v57
	v_cmp_eq_u32_e64 s[34:35], 0, v73
	v_bitop3_b32 v73, v120, s83, v117 bitop3:0xc8
	v_max3_f32 v72, v72, v62, v63
	v_cndmask_b32_e64 v56, v241, v56, s[16:17]
	v_cndmask_b32_e64 v57, v241, v57, s[14:15]
	v_mul_f32_e32 v58, 0x3e38aa3b, v58
	v_mul_f32_e32 v59, 0x3e38aa3b, v59
	v_cmp_eq_u32_e64 s[30:31], 0, v73
	v_bitop3_b32 v73, v122, s50, v121 bitop3:0xc8
	v_max3_f32 v72, v72, v56, v57
	v_cndmask_b32_e64 v58, v58, v241, s[36:37]
	v_cndmask_b32_e64 v59, v59, v241, s[26:27]
	v_mul_f32_e32 v68, 0x3e38aa3b, v68
	v_mul_f32_e32 v69, 0x3e38aa3b, v69
	v_cmp_eq_u32_e64 s[28:29], 0, v73
	v_bitop3_b32 v73, v122, s82, v121 bitop3:0xc8
	v_max3_f32 v72, v72, v58, v59
	v_cndmask_b32_e64 v68, v68, v241, s[34:35]
	v_cndmask_b32_e64 v69, v69, v241, s[30:31]
	v_mul_f32_e32 v70, 0x3e38aa3b, v70
	v_cmp_eq_u32_e64 s[24:25], 0, v73
	v_mul_f32_e32 v71, 0x3e38aa3b, v71
	v_max3_f32 v72, v72, v68, v69
	v_cndmask_b32_e64 v70, v70, v241, s[28:29]
	v_cndmask_b32_e64 v71, v71, v241, s[24:25]
	v_max3_f32 v72, v72, v70, v71
	ds_bpermute_b32 v73, v109, v72
	s_waitcnt lgkmcnt(0)
	v_max_f32_e32 v73, v73, v73
	v_max_f32_e32 v72, v72, v73
	ds_bpermute_b32 v73, v108, v72
	s_waitcnt lgkmcnt(0)
	v_max3_f32 v117, v118, v72, v73
	v_sub_f32_e32 v57, v57, v117
	v_exp_f32_e32 v57, v57
	v_sub_f32_e32 v64, v64, v117
	v_exp_f32_e32 v64, v64
	v_sub_f32_e32 v65, v65, v117
	v_cndmask_b32_e64 v75, 0, v57, s[14:15]
	v_sub_f32_e32 v57, v58, v117
	v_exp_f32_e32 v57, v57
	v_exp_f32_e32 v65, v65
	v_sub_f32_e32 v66, v66, v117
	v_exp_f32_e32 v66, v66
	v_cndmask_b32_e64 v76, v57, 0, s[36:37]
	v_sub_f32_e32 v57, v59, v117
	v_exp_f32_e32 v57, v57
	v_sub_f32_e32 v67, v67, v117
	v_exp_f32_e32 v67, v67
	v_sub_f32_e32 v60, v60, v117
	v_cndmask_b32_e64 v77, v57, 0, s[26:27]
	v_sub_f32_e32 v57, v68, v117
	v_exp_f32_e32 v57, v57
	v_cndmask_b32_e64 v73, 0, v64, s[22:23]
	v_exp_f32_e32 v60, v60
	v_sub_f32_e32 v61, v61, v117
	v_cndmask_b32_e64 v68, v57, 0, s[34:35]
	v_sub_f32_e32 v57, v69, v117
	v_add_f32_e32 v64, 0, v73
	v_cndmask_b32_e64 v65, v65, 0, s[20:21]
	v_exp_f32_e32 v61, v61
	v_sub_f32_e32 v62, v62, v117
	v_exp_f32_e32 v57, v57
	v_add_f32_e32 v64, v65, v64
	v_cndmask_b32_e64 v66, v66, 0, s[12:13]
	v_exp_f32_e32 v62, v62
	v_sub_f32_e32 v63, v63, v117
	v_add_f32_e32 v64, v66, v64
	v_cndmask_b32_e64 v67, v67, 0, s[18:19]
	v_exp_f32_e32 v63, v63
	v_sub_f32_e32 v56, v56, v117
	v_add_f32_e32 v64, v67, v64
	v_cndmask_b32_e64 v60, v60, 0, s[6:7]
	v_exp_f32_e32 v56, v56
	v_add_f32_e32 v64, v60, v64
	v_cndmask_b32_e64 v61, v61, 0, s[10:11]
	v_cndmask_b32_e64 v69, v57, 0, s[30:31]
	v_sub_f32_e32 v57, v70, v117
	v_add_f32_e32 v64, v61, v64
	v_cndmask_b32_e64 v62, v62, 0, s[8:9]
	v_exp_f32_e32 v57, v57
	v_add_f32_e32 v64, v62, v64
	v_cndmask_b32_e64 v63, v63, 0, vcc
	v_add_f32_e32 v64, v63, v64
	v_cndmask_b32_e64 v74, 0, v56, s[16:17]
	v_add_f32_e32 v56, v74, v64
	v_add_f32_e32 v56, v75, v56
	v_cndmask_b32_e64 v70, v57, 0, s[28:29]
	v_sub_f32_e32 v57, v71, v117
	v_sub_f32_e32 v72, v118, v117
	v_add_f32_e32 v56, v76, v56
	v_exp_f32_e32 v57, v57
	v_add_f32_e32 v56, v77, v56
	v_exp_f32_e32 v64, v72
	v_add_f32_e32 v56, v68, v56
	v_add_f32_e32 v56, v69, v56
	v_add_f32_e32 v56, v70, v56
	v_cndmask_b32_e64 v71, v57, 0, s[24:25]
	v_add_f32_e32 v114, v71, v56
	v_cvt_pk_bf16_f32 v56, v73, v65
	v_cvt_pk_bf16_f32 v57, v66, v67
	v_cvt_pk_bf16_f32 v58, v60, v61
	v_cvt_pk_bf16_f32 v59, v62, v63
	v_pk_mul_f32 v[10:11], v[10:11], v[64:65] op_sel_hi:[1,0]
	v_pk_mul_f32 v[8:9], v[8:9], v[64:65] op_sel_hi:[1,0]
	v_pk_mul_f32 v[14:15], v[14:15], v[64:65] op_sel_hi:[1,0]
	v_pk_mul_f32 v[12:13], v[12:13], v[64:65] op_sel_hi:[1,0]
	v_pk_mul_f32 v[6:7], v[6:7], v[64:65] op_sel_hi:[1,0]
	v_pk_mul_f32 v[4:5], v[4:5], v[64:65] op_sel_hi:[1,0]
	v_pk_mul_f32 v[2:3], v[2:3], v[64:65] op_sel_hi:[1,0]
	v_pk_mul_f32 v[0:1], v[0:1], v[64:65] op_sel_hi:[1,0]
	v_mfma_f32_16x16x32_bf16 v[8:11], v[52:55], v[56:59], v[8:11]
	v_cvt_pk_bf16_f32 v60, v74, v75
	v_cvt_pk_bf16_f32 v61, v76, v77
	v_cvt_pk_bf16_f32 v62, v68, v69
	v_mfma_f32_16x16x32_bf16 v[12:15], v[44:47], v[56:59], v[12:15]
	v_cvt_pk_bf16_f32 v63, v70, v71
	v_fmac_f32_e32 v114, v119, v64
	v_mfma_f32_16x16x32_bf16 v[4:7], v[36:39], v[56:59], v[4:7]
	v_mfma_f32_16x16x32_bf16 v[0:3], v[24:27], v[56:59], v[0:3]
	v_mfma_f32_16x16x32_bf16 v[8:11], v[48:51], v[60:63], v[8:11]
	v_mfma_f32_16x16x32_bf16 v[12:15], v[40:43], v[60:63], v[12:15]
	v_mfma_f32_16x16x32_bf16 v[4:7], v[32:35], v[60:63], v[4:7]
	v_mfma_f32_16x16x32_bf16 v[0:3], v[28:31], v[60:63], v[0:3]
	s_cbranch_scc0 .LBB0_619
	s_branch .LBB0_623

.LBB0_626:
	s_lshl_b64 s[8:9], s[92:93], 17
	v_lshl_add_u64 v[42:43], v[48:49], 0, s[8:9]
	v_lshl_add_u64 v[46:47], v[212:213], 1, v[42:43]
	global_load_dwordx4 v[42:45], v[46:47], off
	v_add_co_u32_e32 v74, vcc, s82, v46
	v_add_u32_e32 v100, 0x41, v65
	s_nop 0
	v_addc_co_u32_e32 v75, vcc, 0, v47, vcc
	global_load_dwordx4 v[56:59], v[74:75], off
	v_add_co_u32_e32 v78, vcc, s94, v46
	v_add_u32_e32 v101, 64, v65
	s_nop 0
	v_addc_co_u32_e32 v79, vcc, 0, v47, vcc
	global_load_dwordx4 v[60:63], v[78:79], off
	v_add_co_u32_e32 v82, vcc, s51, v46
	v_cmp_gt_u32_e64 s[22:23], s47, v100
	s_nop 0
	v_addc_co_u32_e32 v83, vcc, 0, v47, vcc
	global_load_dwordx4 v[66:69], v[82:83], off
	v_lshl_add_u64 v[236:237], v[46:47], 0, v[232:233]
	global_load_dwordx4 v[70:73], v[236:237], off
	s_nop 0
	v_lshl_add_u64 v[236:237], v[74:75], 0, v[232:233]
	global_load_dwordx4 v[74:77], v[236:237], off
	s_nop 0
	v_lshl_add_u64 v[236:237], v[78:79], 0, v[232:233]
	global_load_dwordx4 v[78:81], v[236:237], off
	s_nop 0
	v_lshl_add_u64 v[236:237], v[82:83], 0, v[232:233]
	global_load_dwordx4 v[82:85], v[236:237], off
	v_add_u32_e32 v103, 51, v65
	v_cndmask_b32_e64 v122, 0, v246, s[22:23]
	v_cmp_gt_u32_e64 s[22:23], s47, v101
	v_add_u32_e32 v104, 50, v65
	v_add_u32_e32 v105, 49, v65
	v_cndmask_b32_e64 v123, 0, v247, s[22:23]
	v_cmp_gt_u32_e64 s[22:23], s47, v103
	s_mov_b32 s7, s93
	v_add_u32_e32 v41, 0x63, v65
	v_cndmask_b32_e64 v103, 0, v248, s[22:23]
	v_cmp_gt_u32_e64 s[22:23], s47, v104
	v_add_u32_e32 v96, 0x51, v65
	v_add_u32_e32 v97, 0x50, v65
	v_add_u32_e32 v106, 48, v65
	v_cndmask_b32_e64 v104, 0, v249, s[22:23]
	v_cmp_gt_u32_e64 s[22:23], s47, v105
	v_cmp_gt_u32_e32 vcc, s88, v64
	v_add_u32_e32 v86, 0x61, v65
	v_add_u32_e32 v87, 0x60, v65
	v_lshl_add_u64 v[46:47], s[6:7], 1, v[50:51]
	v_cmp_lt_u32_e64 s[12:13], s49, v96
	v_cmp_lt_u32_e64 s[14:15], s49, v97
	v_cndmask_b32_e64 v105, 0, v250, s[22:23]
	v_cmp_gt_u32_e64 s[22:23], s47, v106
	v_cmp_gt_u32_e64 s[30:31], s47, v41
	v_cndmask_b32_e64 v102, 2, 0, vcc
	v_add_u32_e32 v94, 0x53, v65
	v_add_u32_e32 v95, 0x52, v65
	v_cmp_lt_u32_e64 s[20:21], s49, v86
	v_cmp_lt_u32_e64 s[16:17], s49, v87
	v_cndmask_b32_e64 v118, 64, 0, s[12:13]
	v_cndmask_b32_e64 v119, v244, 0, s[14:15]
	v_cndmask_b32_e64 v106, 0, v251, s[22:23]
	v_add_co_u32_e64 v86, s[22:23], s0, v46
	v_add_u32_e32 v98, 0x43, v65
	v_add_u32_e32 v99, 0x42, v65
	v_cndmask_b32_e64 v107, 4, 0, s[20:21]
	v_cndmask_b32_e64 v111, 8, 0, s[16:17]
	v_cmp_lt_u32_e64 s[18:19], s49, v94
	v_cmp_lt_u32_e64 s[10:11], s49, v95
	v_addc_co_u32_e64 v87, s[22:23], 0, v47, s[22:23]
	v_or3_b32 v102, v102, v118, v119
	v_cndmask_b32_e64 v112, 16, 0, s[18:19]
	v_cndmask_b32_e64 v113, 32, 0, s[10:11]
	v_cmp_gt_u32_e64 s[6:7], s47, v98
	v_cmp_gt_u32_e64 s[8:9], s47, v99
	global_load_dwordx4 v[94:97], v[46:47], off
	v_lshl_add_u64 v[236:237], v[46:47], 0, v[214:215]
	global_load_dwordx4 v[98:101], v[236:237], off
	v_cndmask_b32_e64 v120, 0, v245, s[6:7]
	v_cndmask_b32_e64 v121, 0, v240, s[8:9]
	v_or_b32_e32 v118, v122, v123
	v_or_b32_e32 v103, v103, v104
	v_or_b32_e32 v104, v105, v106
	s_mov_b32 s38, 0x40000
	s_cmp_ge_i32 s45, s54
	s_waitcnt vmcnt(0) lgkmcnt(0)
	ds_write_b128 v234, v[42:45]
	ds_write_b128 v234, v[70:73] offset:1280
	ds_write_b128 v234, v[56:59] offset:2560
	ds_write_b128 v234, v[74:77] offset:3840
	ds_write_b128 v234, v[60:63] offset:5120
	ds_write_b128 v234, v[78:81] offset:6400
	ds_write_b128 v234, v[66:69] offset:7680
	ds_write_b128 v234, v[82:85] offset:8960
	ds_read_b128 v[42:45], v235
	ds_read_b128 v[70:73], v235 offset:64
	ds_read_b128 v[56:59], v235 offset:2560
	ds_read_b128 v[74:77], v235 offset:2624
	ds_read_b128 v[60:63], v235 offset:5120
	ds_read_b128 v[78:81], v235 offset:5184
	ds_read_b128 v[66:69], v235 offset:7680
	ds_read_b128 v[82:85], v235 offset:7744
	ds_write_b128 v234, v[94:97]
	ds_write_b128 v234, v[98:101] offset:1280
	ds_read_b128 v[94:97], v235
	ds_read_b128 v[98:101], v235 offset:64
	s_waitcnt lgkmcnt(4)
	v_mfma_f32_16x16x32_bf16 v[66:69], v[66:69], v[32:35], 0
	v_mfma_f32_16x16x32_bf16 v[42:45], v[42:45], v[32:35], 0
	v_mfma_f32_16x16x32_bf16 v[56:59], v[56:59], v[32:35], 0
	v_mfma_f32_16x16x32_bf16 v[42:45], v[70:73], v[36:39], v[42:45]
	v_mfma_f32_16x16x32_bf16 v[60:63], v[60:63], v[32:35], 0
	v_mfma_f32_16x16x32_bf16 v[56:59], v[74:77], v[36:39], v[56:59]
	s_nop 5
	v_mul_f32_e32 v42, 0x3e38aa3b, v42
	v_cndmask_b32_e64 v41, v241, v42, s[30:31]
	v_mul_f32_e32 v42, 0x3e38aa3b, v43
	v_mul_f32_e32 v43, 0x3e38aa3b, v44
	v_mfma_f32_16x16x32_bf16 v[66:69], v[82:85], v[36:39], v[66:69]
	v_cndmask_b32_e64 v83, v43, v241, s[20:21]
	v_mul_f32_e32 v43, 0x3e38aa3b, v45
	global_load_dwordx4 v[70:73], v[86:87], off
	v_lshl_add_u64 v[236:237], v[86:87], 0, v[214:215]
	global_load_dwordx4 v[74:77], v[236:237], off
	v_or3_b32 v86, v107, v111, v102
	v_mfma_f32_16x16x32_bf16 v[60:63], v[78:81], v[36:39], v[60:63]
	v_cndmask_b32_e64 v84, v43, v241, s[16:17]
	v_mul_f32_e32 v43, 0x3e38aa3b, v56
	v_or3_b32 v86, v112, v113, v86
	v_cndmask_b32_e64 v85, v43, v241, s[18:19]
	v_mul_f32_e32 v43, 0x3e38aa3b, v57
	v_or3_b32 v78, v120, v86, v121
	v_cndmask_b32_e64 v86, v43, v241, s[10:11]
	v_mul_f32_e32 v43, 0x3e38aa3b, v58
	v_cndmask_b32_e64 v87, v43, v241, s[12:13]
	v_mul_f32_e32 v43, 0x3e38aa3b, v59
	v_cndmask_b32_e64 v102, v43, v241, s[14:15]
	v_mul_f32_e32 v43, 0x3e38aa3b, v60
	v_cndmask_b32_e64 v105, v241, v43, s[6:7]
	v_mul_f32_e32 v43, 0x3e38aa3b, v61
	v_cndmask_b32_e32 v82, v42, v241, vcc
	v_cndmask_b32_e64 v106, v241, v43, s[8:9]
	v_bitop3_b32 v43, v118, s95, v78 bitop3:0xc8
	v_or_b32_e32 v79, v118, v78
	v_max3_f32 v42, v41, s71, v82
	v_mul_f32_e32 v44, 0x3e38aa3b, v62
	v_cmp_eq_u32_e64 s[26:27], 0, v43
	v_bitop3_b32 v43, v118, s48, v78 bitop3:0xc8
	v_max3_f32 v42, v42, v83, v84
	v_cndmask_b32_e64 v107, v44, v241, s[26:27]
	v_mul_f32_e32 v44, 0x3e38aa3b, v63
	v_cmp_eq_u32_e64 s[34:35], 0, v43
	v_bitop3_b32 v43, v103, s90, v79 bitop3:0xc8
	v_or_b32_e32 v80, v103, v79
	v_max3_f32 v42, v42, v85, v86
	v_cndmask_b32_e64 v111, v44, v241, s[34:35]
	v_mul_f32_e32 v44, 0x3e38aa3b, v66
	v_cmp_eq_u32_e64 s[22:23], 0, v43
	v_bitop3_b32 v43, v103, s83, v79 bitop3:0xc8
	v_max3_f32 v42, v42, v87, v102
	v_cndmask_b32_e64 v66, v44, v241, s[22:23]
	v_mul_f32_e32 v44, 0x3e38aa3b, v67
	v_cmp_eq_u32_e64 s[24:25], 0, v43
	v_bitop3_b32 v43, v104, s50, v80 bitop3:0xc8
	v_max3_f32 v42, v42, v105, v106
	v_cndmask_b32_e64 v103, v44, v241, s[24:25]
	v_mul_f32_e32 v44, 0x3e38aa3b, v68
	v_cmp_eq_u32_e64 s[28:29], 0, v43
	v_bitop3_b32 v43, v104, s82, v80 bitop3:0xc8
	v_max3_f32 v42, v42, v107, v111
	v_cndmask_b32_e64 v68, v44, v241, s[28:29]
	v_mul_f32_e32 v44, 0x3e38aa3b, v69
	v_cmp_eq_u32_e64 s[36:37], 0, v43
	v_max3_f32 v42, v42, v66, v103
	v_add_co_u32_e64 v56, s[38:39], s38, v46
	v_cndmask_b32_e64 v69, v44, v241, s[36:37]
	v_max3_f32 v60, v42, v68, v69
	ds_bpermute_b32 v61, v109, v60
	v_addc_co_u32_e64 v57, s[38:39], 0, v47, s[38:39]
	v_add_co_u32_e64 v46, s[38:39], s76, v46
	s_waitcnt lgkmcnt(0)
	v_max_f32_e32 v61, v61, v61
	v_max_f32_e32 v60, v60, v61
	ds_bpermute_b32 v61, v108, v60
	v_addc_co_u32_e64 v47, s[38:39], 0, v47, s[38:39]
	global_load_dwordx4 v[42:45], v[56:57], off
	s_nop 0
	v_lshl_add_u64 v[236:237], v[56:57], 0, v[214:215]
	global_load_dwordx4 v[56:59], v[236:237], off
	s_waitcnt lgkmcnt(0)
	v_max3_f32 v67, v117, v60, v61
	global_load_dwordx4 v[60:63], v[46:47], off
	v_lshl_add_u64 v[236:237], v[46:47], 0, v[214:215]
	global_load_dwordx4 v[78:81], v[236:237], off
	v_sub_f32_e32 v47, v82, v67
	v_sub_f32_e32 v82, v83, v67
	v_exp_f32_e32 v82, v82
	v_sub_f32_e32 v41, v41, v67
	v_exp_f32_e32 v41, v41
	v_exp_f32_e32 v47, v47
	v_cndmask_b32_e64 v104, v82, 0, s[20:21]
	v_sub_f32_e32 v82, v84, v67
	v_exp_f32_e32 v82, v82
	v_cndmask_b32_e64 v41, 0, v41, s[30:31]
	v_add_f32_e32 v83, 0, v41
	v_cndmask_b32_e64 v47, v47, 0, vcc
	v_add_f32_e32 v83, v47, v83
	v_sub_f32_e32 v84, v85, v67
	v_add_f32_e32 v83, v104, v83
	v_cndmask_b32_e64 v85, v82, 0, s[16:17]
	v_exp_f32_e32 v84, v84
	v_add_f32_e32 v82, v85, v83
	v_sub_f32_e32 v83, v86, v67
	v_exp_f32_e32 v83, v83
	v_cndmask_b32_e64 v84, v84, 0, s[18:19]
	v_add_f32_e32 v82, v84, v82
	v_sub_f32_e32 v86, v87, v67
	v_sub_f32_e32 v87, v102, v67
	v_cndmask_b32_e64 v102, v83, 0, s[10:11]
	v_add_f32_e32 v112, v102, v82
	v_sub_f32_e32 v82, v105, v67
	v_exp_f32_e32 v82, v82
	v_exp_f32_e32 v86, v86
	v_sub_f32_e32 v105, v107, v67
	v_exp_f32_e32 v87, v87
	v_cndmask_b32_e64 v107, 0, v82, s[6:7]
	v_sub_f32_e32 v82, v103, v67
	v_exp_f32_e32 v82, v82
	v_sub_f32_e32 v46, v117, v67
	v_sub_f32_e32 v83, v106, v67
	v_exp_f32_e32 v83, v83
	v_exp_f32_e32 v46, v46
	v_cndmask_b32_e64 v86, v86, 0, s[12:13]
	v_exp_f32_e32 v105, v105
	v_sub_f32_e32 v106, v111, v67
	v_cndmask_b32_e64 v87, v87, 0, s[14:15]
	v_exp_f32_e32 v106, v106
	v_sub_f32_e32 v66, v66, v67
	v_sub_f32_e32 v68, v68, v67
	v_sub_f32_e32 v69, v69, v67
	v_cndmask_b32_e64 v117, v82, 0, s[24:25]
	v_cvt_pk_bf16_f32 v82, v41, v47
	v_add_f32_e32 v41, v86, v112
	v_exp_f32_e32 v66, v66
	v_exp_f32_e32 v68, v68
	v_exp_f32_e32 v69, v69
	v_add_f32_e32 v41, v87, v41
	v_cndmask_b32_e64 v111, 0, v83, s[8:9]
	v_cvt_pk_bf16_f32 v83, v104, v85
	v_cvt_pk_bf16_f32 v84, v84, v102
	v_cvt_pk_bf16_f32 v85, v86, v87
	v_pk_mul_f32 v[30:31], v[30:31], v[46:47] op_sel_hi:[1,0]
	v_pk_mul_f32 v[28:29], v[28:29], v[46:47] op_sel_hi:[1,0]
	v_pk_mul_f32 v[26:27], v[26:27], v[46:47] op_sel_hi:[1,0]
	v_pk_mul_f32 v[24:25], v[24:25], v[46:47] op_sel_hi:[1,0]
	v_add_f32_e32 v41, v107, v41
	v_pk_mul_f32 v[22:23], v[22:23], v[46:47] op_sel_hi:[1,0]
	v_pk_mul_f32 v[20:21], v[20:21], v[46:47] op_sel_hi:[1,0]
	v_pk_mul_f32 v[18:19], v[18:19], v[46:47] op_sel_hi:[1,0]
	v_pk_mul_f32 v[16:17], v[16:17], v[46:47] op_sel_hi:[1,0]
	v_cndmask_b32_e64 v113, v105, 0, s[26:27]
	v_mfma_f32_16x16x32_bf16 v[28:31], v[94:97], v[82:85], v[28:31]
	v_add_f32_e32 v41, v111, v41
	v_cndmask_b32_e64 v106, v106, 0, s[34:35]
	v_add_f32_e32 v41, v113, v41
	s_waitcnt vmcnt(0)
	ds_write_b128 v234, v[70:73]
	ds_write_b128 v234, v[74:77] offset:1280
	ds_write_b128 v234, v[42:45] offset:2560
	ds_write_b128 v234, v[56:59] offset:3840
	ds_write_b128 v234, v[60:63] offset:5120
	ds_write_b128 v234, v[78:81] offset:6400
	ds_read_b128 v[70:73], v235
	ds_read_b128 v[74:77], v235 offset:64
	ds_read_b128 v[42:45], v235 offset:2560
	ds_read_b128 v[56:59], v235 offset:2624
	ds_read_b128 v[60:63], v235 offset:5120
	ds_read_b128 v[78:81], v235 offset:5184
	s_waitcnt lgkmcnt(0)
	v_mfma_f32_16x16x32_bf16 v[24:27], v[70:73], v[82:85], v[24:27]
	v_cndmask_b32_e64 v66, v66, 0, s[22:23]
	v_cndmask_b32_e64 v68, v68, 0, s[28:29]
	v_cndmask_b32_e64 v69, v69, 0, s[36:37]
	v_mfma_f32_16x16x32_bf16 v[20:23], v[42:45], v[82:85], v[20:23]
	v_add_f32_e32 v41, v106, v41
	v_cvt_pk_bf16_f32 v102, v107, v111
	v_cvt_pk_bf16_f32 v103, v113, v106
	s_waitcnt lgkmcnt(0)
	v_mfma_f32_16x16x32_bf16 v[16:19], v[60:63], v[82:85], v[16:19]
	v_cvt_pk_bf16_f32 v104, v66, v117
	v_cvt_pk_bf16_f32 v105, v68, v69
	v_add_f32_e32 v41, v66, v41
	v_add_f32_e32 v41, v117, v41
	v_mfma_f32_16x16x32_bf16 v[28:31], v[98:101], v[102:105], v[28:31]
	v_add_f32_e32 v41, v68, v41
	v_add_f32_e32 v66, v69, v41
	v_fmac_f32_e32 v66, v40, v46
	v_mfma_f32_16x16x32_bf16 v[24:27], v[74:77], v[102:105], v[24:27]
	v_mfma_f32_16x16x32_bf16 v[20:23], v[56:59], v[102:105], v[20:23]
	v_mfma_f32_16x16x32_bf16 v[16:19], v[78:81], v[102:105], v[16:19]
	s_cbranch_scc0 .LBB0_625
